# baseline (speedup 1.0000x reference)
; __device__ void attn_a_item(const Params& p, int layer, int b, int h, int q128, unsigned char* smem) {
;     ...
;     if (strm == 0) {
; #pragma unroll
;         for (int mp = 0; mp < 2; ++mp)
; #pragma unroll
;             for (int qt = 0; qt < 2; ++qt) {
; #pragma unroll
;                 for (int et = 0; et < 4; ++et)
; #pragma unroll
;                     for (int r = 0; r < 4; ++r) o[mp][qt][et][r] += cmb[(((mp * 2 + qt) * 4 + et) * 4 + r) * 64];
;                 ls[mp][qt][0] += cmb[(64 + mp * 2 + qt) * 64];
;             }
;         const float lam = reinterpret_cast<const float*>(p.ws + WS_LAM)[layer];
;         const float lam_init = 0.8f - 0.6f * expf(-0.3f * (float)layer);
;         bf16_t* mix = reinterpret_cast<bf16_t*>(p.ws + WS_MIX);
; #pragma unroll
;         for (int qt = 0; qt < 2; ++qt) {
;             const float l0 = ls[0][qt][0], l1 = ls[1][qt][0];
;             const float i0 = 1.f / l0, i1 = lam / l1;
.LBB0_454:
	s_or_b64 exec, exec, s[2:3]
	s_movk_i32 s2, 0x100
	v_cmp_gt_u32_e32 vcc, s2, v172
	s_waitcnt lgkmcnt(0)
	s_barrier
	s_and_saveexec_b64 s[4:5], vcc
	s_cbranch_execz .LBB0_382
	ds_read2st64_b32 v[120:121], v0 offset1:1
	ds_read2st64_b32 v[2:3], v0 offset0:2 offset1:3
	ds_read2st64_b32 v[112:113], v0 offset0:4 offset1:5
	ds_read2st64_b32 v[116:117], v0 offset0:6 offset1:7
	ds_read2st64_b32 v[104:105], v0 offset0:8 offset1:9
	ds_read2st64_b32 v[110:111], v0 offset0:10 offset1:11
	ds_read2st64_b32 v[130:131], v0 offset0:12 offset1:13
	ds_read2st64_b32 v[132:133], v0 offset0:14 offset1:15
	ds_read2st64_b32 v[4:5], v0 offset0:64 offset1:65
	s_waitcnt lgkmcnt(7)
	v_pk_add_f32 v[2:3], v[74:75], v[2:3]
	s_waitcnt lgkmcnt(6)
	v_pk_add_f32 v[64:65], v[64:65], v[112:113]
	s_waitcnt lgkmcnt(5)
	v_pk_add_f32 v[66:67], v[66:67], v[116:117]
	v_pk_add_f32 v[72:73], v[72:73], v[120:121]
	s_waitcnt lgkmcnt(0)
	v_add_f32_e32 v85, v96, v4
	ds_read2st64_b32 v[86:87], v0 offset0:16 offset1:17
	ds_read2st64_b32 v[90:91], v0 offset0:18 offset1:19
	ds_read2st64_b32 v[12:13], v0 offset0:20 offset1:21
	ds_read2st64_b32 v[16:17], v0 offset0:22 offset1:23
	ds_read2st64_b32 v[6:7], v0 offset0:24 offset1:25
	ds_read2st64_b32 v[8:9], v0 offset0:26 offset1:27
	ds_read2st64_b32 v[98:99], v0 offset0:28 offset1:29
	ds_read2st64_b32 v[96:97], v0 offset0:30 offset1:31
	v_add_f32_e32 v127, v92, v5
	ds_read2st64_b32 v[122:123], v0 offset0:32 offset1:33
	ds_read2st64_b32 v[4:5], v0 offset0:34 offset1:35
	ds_read2st64_b32 v[114:115], v0 offset0:36 offset1:37
	ds_read2st64_b32 v[118:119], v0 offset0:38 offset1:39
	ds_read2st64_b32 v[106:107], v0 offset0:40 offset1:41
	ds_read2st64_b32 v[108:109], v0 offset0:42 offset1:43
	ds_read2st64_b32 v[134:135], v0 offset0:44 offset1:45
	ds_read2st64_b32 v[136:137], v0 offset0:46 offset1:47
	ds_read2st64_b32 v[124:125], v0 offset0:66 offset1:67
	s_waitcnt lgkmcnt(7)
	v_pk_add_f32 v[4:5], v[70:71], v[4:5]
	s_waitcnt lgkmcnt(6)
	v_pk_add_f32 v[60:61], v[60:61], v[114:115]
	s_waitcnt lgkmcnt(5)
	v_pk_add_f32 v[62:63], v[62:63], v[118:119]
	v_pk_add_f32 v[68:69], v[68:69], v[122:123]
	s_waitcnt lgkmcnt(0)
	v_add_f32_e32 v126, v88, v124
	ds_read2st64_b32 v[92:93], v0 offset0:48 offset1:49
	ds_read2st64_b32 v[94:95], v0 offset0:50 offset1:51
	ds_read2st64_b32 v[18:19], v0 offset0:52 offset1:53
	ds_read2st64_b32 v[88:89], v0 offset0:54 offset1:55
	ds_read2st64_b32 v[10:11], v0 offset0:56 offset1:57
	ds_read2st64_b32 v[14:15], v0 offset0:58 offset1:59
	ds_read2st64_b32 v[102:103], v0 offset0:60 offset1:61
	ds_read2st64_b32 v[100:101], v0 offset0:62 offset1:63
	global_load_dword v129, v1, s[76:77]
	v_add_f32_e32 v125, v84, v125
	v_div_scale_f32 v84, s[6:7], v85, v85, 1.0
	v_rcp_f32_e32 v124, v84
	s_waitcnt lgkmcnt(7)
	v_pk_add_f32 v[36:37], v[36:37], v[92:93]
	v_pk_add_f32 v[40:41], v[40:41], v[86:87]
	s_waitcnt lgkmcnt(6)
	v_pk_add_f32 v[38:39], v[38:39], v[94:95]
	v_fma_f32 v128, -v84, v124, 1.0
	v_fmac_f32_e32 v124, v128, v124
	v_div_scale_f32 v128, vcc, 1.0, v85, 1.0
	v_mul_f32_e32 v138, v128, v124
	v_fma_f32 v139, -v84, v138, v128
	v_fmac_f32_e32 v138, v139, v124
	v_fma_f32 v84, -v84, v138, v128
	v_div_fmas_f32 v84, v84, v124, v138
	v_div_fixup_f32 v124, v84, v85, 1.0
	v_pk_add_f32 v[42:43], v[42:43], v[90:91]
	s_waitcnt lgkmcnt(5)
	v_pk_add_f32 v[18:19], v[28:29], v[18:19]
	v_pk_add_f32 v[6:7], v[24:25], v[6:7]
	v_pk_add_f32 v[12:13], v[32:33], v[12:13]
	s_waitcnt lgkmcnt(2)
	v_pk_add_f32 v[14:15], v[22:23], v[14:15]
	v_pk_add_f32 v[30:31], v[30:31], v[88:89]
	v_pk_add_f32 v[10:11], v[20:21], v[10:11]
	v_pk_add_f32 v[52:53], v[52:53], v[106:107]
	v_pk_add_f32 v[16:17], v[34:35], v[16:17]
	v_pk_add_f32 v[56:57], v[56:57], v[104:105]
	v_pk_add_f32 v[8:9], v[26:27], v[8:9]
	v_pk_add_f32 v[54:55], v[54:55], v[108:109]
	v_pk_add_f32 v[58:59], v[58:59], v[110:111]
	v_pk_add_f32 v[76:77], v[76:77], v[134:135]
	s_waitcnt lgkmcnt(1)
	v_pk_add_f32 v[44:45], v[44:45], v[102:103]
	v_pk_add_f32 v[80:81], v[80:81], v[130:131]
	v_pk_add_f32 v[48:49], v[48:49], v[98:99]
	v_pk_add_f32 v[78:79], v[78:79], v[136:137]
	s_waitcnt lgkmcnt(0)
	v_pk_add_f32 v[46:47], v[46:47], v[100:101]
	v_pk_add_f32 v[50:51], v[50:51], v[96:97]
	s_lshl_b32 s2, s55, 14
	v_or3_b32 v0, s2, v171, v157
	s_lshl_b32 s2, s54, 1
	v_readlane_b32 s3, v254, 18
	s_add_u32 s2, s3, s2
	v_readlane_b32 s3, v254, 19
	s_addc_u32 s3, s3, 0
	v_lshlrev_b32_e32 v0, 11, v0
	v_mov_b32_e32 v157, v1
	s_waitcnt vmcnt(0)
; __device__ void attn_a_item(const Params& p, int layer, int b, int h, int q128, unsigned char* smem) {
;     ...
;         const float lam = reinterpret_cast<const float*>(p.ws + WS_LAM)[layer];
;         const float lam_init = 0.8f - 0.6f * expf(-0.3f * (float)layer);
;         bf16_t* mix = reinterpret_cast<bf16_t*>(p.ws + WS_MIX);
; #pragma unroll
;         for (int qt = 0; qt < 2; ++qt) {
;             const float l0 = ls[0][qt][0], l1 = ls[1][qt][0];
;             const float i0 = 1.f / l0, i1 = lam / l1;
;             float y[4][4], ss = 0.f;
; #pragma unroll
;             for (int et = 0; et < 4; ++et)
; #pragma unroll
;                 for (int r = 0; r < 4; ++r) { y[et][r] = o[0][qt][et][r] * i0 - o[1][qt][et][r] * i1; ss += y[et][r] * y[et][r]; }
;             ss += __shfl_xor(ss, 16); ss += __shfl_xor(ss, 32);
	v_div_scale_f32 v84, s[6:7], v126, v126, v129
	v_rcp_f32_e32 v85, v84
	s_nop 0
	v_fma_f32 v128, -v84, v85, 1.0
	v_fmac_f32_e32 v85, v128, v85
	v_div_scale_f32 v128, vcc, v129, v126, v129
	v_mul_f32_e32 v138, v128, v85
	v_fma_f32 v139, -v84, v138, v128
	v_fmac_f32_e32 v138, v139, v85
	v_fma_f32 v84, -v84, v138, v128
	v_div_fmas_f32 v84, v84, v85, v138
	v_div_fixup_f32 v126, v84, v126, v129
	v_lshlrev_b32_e32 v128, 4, v174
	v_pk_mul_f32 v[4:5], v[4:5], v[126:127] op_sel_hi:[1,0]
	v_pk_mul_f32 v[60:61], v[60:61], v[126:127] op_sel_hi:[1,0]
	v_pk_fma_f32 v[70:71], v[2:3], v[124:125], v[4:5] op_sel_hi:[1,0,1] neg_lo:[0,0,1] neg_hi:[0,0,1]
	global_load_dwordx4 v[2:5], v128, s[50:51]
	v_pk_fma_f32 v[60:61], v[64:65], v[124:125], v[60:61] op_sel_hi:[1,0,1] neg_lo:[0,0,1] neg_hi:[0,0,1]
	v_div_scale_f32 v64, s[6:7], v127, v127, 1.0
	v_rcp_f32_e32 v65, v64
	v_pk_mul_f32 v[62:63], v[62:63], v[126:127] op_sel_hi:[1,0]
	v_pk_mul_f32 v[68:69], v[68:69], v[126:127] op_sel_hi:[1,0]
	v_pk_fma_f32 v[62:63], v[66:67], v[124:125], v[62:63] op_sel_hi:[1,0,1] neg_lo:[0,0,1] neg_hi:[0,0,1]
	v_fma_f32 v66, -v64, v65, 1.0
	v_fmac_f32_e32 v65, v66, v65
	v_div_scale_f32 v66, vcc, 1.0, v127, 1.0
	v_mul_f32_e32 v67, v66, v65
	v_fma_f32 v74, -v64, v67, v66
	v_fmac_f32_e32 v67, v74, v65
	v_fma_f32 v64, -v64, v67, v66
	v_div_fmas_f32 v64, v64, v65, v67
	v_div_scale_f32 v65, s[6:7], v125, v125, v129
	v_rcp_f32_e32 v66, v65
	v_div_fixup_f32 v64, v64, v127, 1.0
	v_pk_fma_f32 v[72:73], v[72:73], v[124:125], v[68:69] op_sel_hi:[1,0,1] neg_lo:[0,0,1] neg_hi:[0,0,1]
	v_mov_b32_e32 v21, v71
	v_fma_f32 v67, -v65, v66, 1.0
	v_fmac_f32_e32 v66, v67, v66
	v_div_scale_f32 v67, vcc, v129, v125, v129
	v_mul_f32_e32 v74, v67, v66
	v_fma_f32 v75, -v65, v74, v67
	v_fmac_f32_e32 v74, v75, v66
	v_fma_f32 v65, -v65, v74, v67
	v_div_fmas_f32 v65, v65, v66, v74
	v_div_fixup_f32 v66, v65, v125, v129
	v_pk_mul_f32 v[36:37], v[36:37], v[66:67] op_sel_hi:[1,0]
	v_pk_mul_f32 v[38:39], v[38:39], v[66:67] op_sel_hi:[1,0]
	v_pk_fma_f32 v[40:41], v[40:41], v[64:65], v[36:37] op_sel_hi:[1,0,1] neg_lo:[0,0,1] neg_hi:[0,0,1]
	v_mov_b32_e32 v25, v73
	v_mov_b32_e32 v24, v41
	v_pk_fma_f32 v[38:39], v[42:43], v[64:65], v[38:39] op_sel_hi:[1,0,1] neg_lo:[0,0,1] neg_hi:[0,0,1]
	v_pk_mul_f32 v[18:19], v[18:19], v[66:67] op_sel_hi:[1,0]
	v_mov_b32_e32 v22, v40
	v_mov_b32_e32 v23, v72
	v_pk_mul_f32 v[24:25], v[24:25], v[24:25]
	v_pk_fma_f32 v[12:13], v[12:13], v[64:65], v[18:19] op_sel_hi:[1,0,1] neg_lo:[0,0,1] neg_hi:[0,0,1]
	v_mov_b32_e32 v18, v38
	v_mov_b32_e32 v19, v70
	v_pk_fma_f32 v[22:23], v[22:23], v[22:23], v[24:25]
	v_mov_b32_e32 v20, v39
	v_pk_fma_f32 v[18:19], v[18:19], v[18:19], v[22:23]
	v_pk_mul_f32 v[30:31], v[30:31], v[66:67] op_sel_hi:[1,0]
	v_pk_fma_f32 v[18:19], v[20:21], v[20:21], v[18:19]
	v_mov_b32_e32 v24, v12
	v_mov_b32_e32 v25, v60
	v_pk_mul_f32 v[52:53], v[52:53], v[126:127] op_sel_hi:[1,0]
	v_pk_fma_f32 v[16:17], v[16:17], v[64:65], v[30:31] op_sel_hi:[1,0,1] neg_lo:[0,0,1] neg_hi:[0,0,1]
	v_pk_mul_f32 v[10:11], v[10:11], v[66:67] op_sel_hi:[1,0]
	v_mov_b32_e32 v26, v13
	v_mov_b32_e32 v27, v61
	v_pk_fma_f32 v[18:19], v[24:25], v[24:25], v[18:19]
	v_pk_fma_f32 v[52:53], v[56:57], v[124:125], v[52:53] op_sel_hi:[1,0,1] neg_lo:[0,0,1] neg_hi:[0,0,1]
	v_pk_fma_f32 v[6:7], v[6:7], v[64:65], v[10:11] op_sel_hi:[1,0,1] neg_lo:[0,0,1] neg_hi:[0,0,1]
	v_mov_b32_e32 v20, v16
	v_mov_b32_e32 v21, v62
	v_pk_fma_f32 v[18:19], v[26:27], v[26:27], v[18:19]
	v_pk_mul_f32 v[54:55], v[54:55], v[126:127] op_sel_hi:[1,0]
	v_pk_mul_f32 v[56:57], v[52:53], v[52:53]
	v_pk_mul_f32 v[14:15], v[14:15], v[66:67] op_sel_hi:[1,0]
	v_pk_mul_f32 v[10:11], v[6:7], v[6:7]
	v_mov_b32_e32 v22, v17
	v_mov_b32_e32 v23, v63
	v_pk_fma_f32 v[18:19], v[20:21], v[20:21], v[18:19]
	v_pk_fma_f32 v[54:55], v[58:59], v[124:125], v[54:55] op_sel_hi:[1,0,1] neg_lo:[0,0,1] neg_hi:[0,0,1]
	v_pk_fma_f32 v[8:9], v[8:9], v[64:65], v[14:15] op_sel_hi:[1,0,1] neg_lo:[0,0,1] neg_hi:[0,0,1]
	v_pk_fma_f32 v[18:19], v[22:23], v[22:23], v[18:19]
	v_mov_b32_e32 v20, v10
	v_mov_b32_e32 v21, v56
	v_pk_mul_f32 v[76:77], v[76:77], v[126:127] op_sel_hi:[1,0]
	v_pk_mul_f32 v[58:59], v[54:55], v[54:55]
	v_pk_mul_f32 v[44:45], v[44:45], v[66:67] op_sel_hi:[1,0]
	v_pk_mul_f32 v[14:15], v[8:9], v[8:9]
	v_pk_add_f32 v[18:19], v[20:21], v[18:19]
	v_mov_b32_e32 v56, v11
	v_pk_fma_f32 v[80:81], v[80:81], v[124:125], v[76:77] op_sel_hi:[1,0,1] neg_lo:[0,0,1] neg_hi:[0,0,1]
	v_pk_fma_f32 v[44:45], v[48:49], v[64:65], v[44:45] op_sel_hi:[1,0,1] neg_lo:[0,0,1] neg_hi:[0,0,1]
	v_pk_add_f32 v[10:11], v[56:57], v[18:19]
	v_mov_b32_e32 v18, v14
	v_mov_b32_e32 v19, v58
	v_pk_mul_f32 v[84:85], v[80:81], v[80:81]
	v_pk_add_f32 v[76:77], v[82:83], v[132:133]
	v_pk_mul_f32 v[78:79], v[78:79], v[126:127] op_sel_hi:[1,0]
	v_pk_mul_f32 v[48:49], v[44:45], v[44:45]
	v_pk_mul_f32 v[46:47], v[46:47], v[66:67] op_sel_hi:[1,0]
	v_pk_add_f32 v[10:11], v[18:19], v[10:11]
	v_mov_b32_e32 v58, v15
	v_pk_fma_f32 v[76:77], v[76:77], v[124:125], v[78:79] op_sel_hi:[1,0,1] neg_lo:[0,0,1] neg_hi:[0,0,1]
	v_pk_fma_f32 v[46:47], v[50:51], v[64:65], v[46:47] op_sel_hi:[1,0,1] neg_lo:[0,0,1] neg_hi:[0,0,1]
	v_pk_add_f32 v[10:11], v[58:59], v[10:11]
	v_mov_b32_e32 v14, v48
	v_mov_b32_e32 v15, v84
	v_pk_mul_f32 v[78:79], v[76:77], v[76:77]
	v_pk_mul_f32 v[50:51], v[46:47], v[46:47]
	v_pk_add_f32 v[10:11], v[14:15], v[10:11]
	v_mov_b32_e32 v84, v49
	v_pk_add_f32 v[10:11], v[84:85], v[10:11]
	v_mov_b32_e32 v14, v50
	v_mov_b32_e32 v15, v78
	v_pk_add_f32 v[10:11], v[14:15], v[10:11]
	v_mov_b32_e32 v78, v51
	v_pk_add_f32 v[10:11], v[78:79], v[10:11]
	global_load_dwordx4 v[18:21], v128, s[50:51] offset:64
	global_load_dwordx4 v[22:25], v128, s[50:51] offset:128
	global_load_dwordx4 v[48:51], v128, s[50:51] offset:192
	ds_bpermute_b32 v15, v170, v11
	ds_bpermute_b32 v14, v170, v10
	v_lshl_add_u64 v[82:83], s[2:3], 0, v[0:1]
	v_or_b32_e32 v0, 0x8000, v0
	v_lshl_add_u64 v[74:75], s[2:3], 0, v[0:1]
	s_mov_b32 s2, 0x3c800000
	s_waitcnt lgkmcnt(0)
; __device__ void attn_a_item(const Params& p, int layer, int b, int h, int q128, unsigned char* smem) {
;     ...
;             ss += __shfl_xor(ss, 16); ss += __shfl_xor(ss, 32);
;             const float rs = rsqrtf(ss * (1.f / 64) + EPS) * (1.f - lam_init);
;             const size_t tok = (size_t)b * SEQ + qw0 + qt * 16 + l15;
; #pragma unroll
;             for (int et = 0; et < 4; ++et) {
;                 const int e = et * 16 + kg * 4;
;                 float4 gg = *reinterpret_cast<const float4*>(reinterpret_cast<const float*>(p.ws + WS_LAM) + SM_DIFF + layer * 64 + e);
;                 u32x2 ov = {pk2(y[et][0] * rs * gg.x, y[et][1] * rs * gg.y), pk2(y[et][2] * rs * gg.z, y[et][3] * rs * gg.w)};
;                 *reinterpret_cast<u32x2*>(mix + tok * D + h * 64 + e) = ov;
;             }
	v_pk_add_f32 v[10:11], v[10:11], v[14:15]
	ds_bpermute_b32 v15, v169, v11
	ds_bpermute_b32 v14, v169, v10
	v_lshl_add_u64 v[68:69], v[82:83], 0, v[156:157]
	v_lshl_add_u64 v[36:37], v[74:75], 0, v[156:157]
	s_waitcnt lgkmcnt(0)
	v_pk_add_f32 v[10:11], v[10:11], v[14:15]
	s_nop 0
	v_pk_fma_f32 v[10:11], v[10:11], s[2:3], v[188:189] op_sel_hi:[1,0,0]
	s_nop 0
	v_mul_f32_e32 v0, 0x4b800000, v11
	v_cmp_gt_f32_e64 s[2:3], s74, v11
	v_cmp_gt_f32_e32 vcc, s74, v10
	s_nop 0
	v_cndmask_b32_e64 v0, v11, v0, s[2:3]
	v_rsq_f32_e32 v0, v0
	s_nop 0
	v_mul_f32_e32 v11, 0x45800000, v0
	v_cndmask_b32_e64 v0, v0, v11, s[2:3]
	v_mul_f32_e32 v0, v168, v0
	s_waitcnt vmcnt(0)
	v_pk_mul_f32 v[14:15], v[72:73], v[0:1] op_sel_hi:[1,0]
	v_pk_mul_f32 v[56:57], v[70:71], v[0:1] op_sel_hi:[1,0]
	v_pk_mul_f32 v[14:15], v[2:3], v[14:15]
	v_pk_mul_f32 v[56:57], v[4:5], v[56:57]
	s_nop 0
	v_cvt_pk_bf16_f32 v26, v14, v15
	v_cvt_pk_bf16_f32 v27, v56, v57
	global_store_dwordx2 v[68:69], v[26:27], off
	v_pk_mul_f32 v[14:15], v[60:61], v[0:1] op_sel_hi:[1,0]
	v_pk_mul_f32 v[56:57], v[62:63], v[0:1] op_sel_hi:[1,0]
	v_pk_mul_f32 v[14:15], v[18:19], v[14:15]
	v_pk_mul_f32 v[56:57], v[20:21], v[56:57]
	s_nop 0
	v_cvt_pk_bf16_f32 v26, v14, v15
	v_cvt_pk_bf16_f32 v27, v56, v57
	global_store_dwordx2 v[68:69], v[26:27], off offset:32
	v_pk_mul_f32 v[14:15], v[52:53], v[0:1] op_sel_hi:[1,0]
	v_pk_mul_f32 v[56:57], v[54:55], v[0:1] op_sel_hi:[1,0]
	v_pk_mul_f32 v[14:15], v[22:23], v[14:15]
	v_pk_mul_f32 v[56:57], v[24:25], v[56:57]
	s_nop 0
	v_cvt_pk_bf16_f32 v26, v14, v15
	v_cvt_pk_bf16_f32 v27, v56, v57
	global_store_dwordx2 v[68:69], v[26:27], off offset:64
	v_pk_mul_f32 v[14:15], v[80:81], v[0:1] op_sel_hi:[1,0]
	v_pk_mul_f32 v[56:57], v[76:77], v[0:1] op_sel_hi:[1,0]
	v_pk_mul_f32 v[14:15], v[48:49], v[14:15]
	v_pk_mul_f32 v[56:57], v[50:51], v[56:57]
	s_nop 0
	v_cvt_pk_bf16_f32 v26, v14, v15
	v_cvt_pk_bf16_f32 v27, v56, v57
	global_store_dwordx2 v[68:69], v[26:27], off offset:96
	v_mul_f32_e32 v0, 0x4b800000, v10
	v_cndmask_b32_e32 v0, v10, v0, vcc
	v_rsq_f32_e32 v0, v0
	s_nop 0
	v_mul_f32_e32 v10, 0x45800000, v0
	v_cndmask_b32_e32 v0, v0, v10, vcc
	v_mul_f32_e32 v0, v168, v0
	v_pk_mul_f32 v[14:15], v[40:41], v[0:1] op_sel_hi:[1,0]
	v_pk_mul_f32 v[56:57], v[38:39], v[0:1] op_sel_hi:[1,0]
	v_pk_mul_f32 v[14:15], v[2:3], v[14:15]
	v_pk_mul_f32 v[56:57], v[4:5], v[56:57]
	s_nop 0
	v_cvt_pk_bf16_f32 v26, v14, v15
	v_cvt_pk_bf16_f32 v27, v56, v57
	global_store_dwordx2 v[36:37], v[26:27], off
	v_pk_mul_f32 v[14:15], v[12:13], v[0:1] op_sel_hi:[1,0]
	v_pk_mul_f32 v[56:57], v[16:17], v[0:1] op_sel_hi:[1,0]
	v_pk_mul_f32 v[14:15], v[18:19], v[14:15]
	v_pk_mul_f32 v[56:57], v[20:21], v[56:57]
	s_nop 0
	v_cvt_pk_bf16_f32 v26, v14, v15
	v_cvt_pk_bf16_f32 v27, v56, v57
	global_store_dwordx2 v[36:37], v[26:27], off offset:32
	v_pk_mul_f32 v[14:15], v[6:7], v[0:1] op_sel_hi:[1,0]
	v_pk_mul_f32 v[56:57], v[8:9], v[0:1] op_sel_hi:[1,0]
	v_pk_mul_f32 v[14:15], v[22:23], v[14:15]
	v_pk_mul_f32 v[56:57], v[24:25], v[56:57]
	s_nop 0
	v_cvt_pk_bf16_f32 v26, v14, v15
	v_cvt_pk_bf16_f32 v27, v56, v57
	global_store_dwordx2 v[36:37], v[26:27], off offset:64
	v_pk_mul_f32 v[14:15], v[44:45], v[0:1] op_sel_hi:[1,0]
	v_pk_mul_f32 v[56:57], v[46:47], v[0:1] op_sel_hi:[1,0]
	v_pk_mul_f32 v[14:15], v[48:49], v[14:15]
	v_pk_mul_f32 v[56:57], v[50:51], v[56:57]
	s_nop 0
	v_cvt_pk_bf16_f32 v26, v14, v15
	v_cvt_pk_bf16_f32 v27, v56, v57
	global_store_dwordx2 v[36:37], v[26:27], off offset:96
	s_branch .LBB0_382
